# MLA loop: trims + scalar (saddr) prefetch addressing + rare rescale path out of line
# speedup vs baseline: 1.0952x; 1.0105x over previous
; DI float bfs2f(short v) { return __uint_as_float(((unsigned)(u16)v) << 16); }
; DI u16 f2bf(float a) { return (u16)(pk2(a, 0.f) & 0xffffu); }
; #define MLA_GLOAD(T) do { rkn = *(const u32x4*)(kvsrc + (size_t)(T) * 64 * KVP); rvv = *(const u32x4*)(kvsrc + (size_t)(T) * 64 * KVP + 64); \
;     if (kr_on) rkr = *(const u32x4*)(krsrc + (size_t)(T) * 64 * 32); } while (0)
; #define MLA_LSTORE(B) do { u16* kd = Kl + (B) * 64 * KP; u16* vd = Vl + (B) * 64 * VP; *(u32x4*)(kd + kdst0) = rkn; *(u32x4*)(vd + vdst) = rvv; \
;     if (kr_on) *(u32x4*)(kd + kdst2) = rkr; } while (0)
; DI void mla_unit(const Params& p, char* lds, int seqbase, int S, int h, int qb) {
;     ...
;   const int pos = qb * 256 + wid * 32 + r32, qrow = seqbase + pos;
;   bf16x8 qf[6];
; #pragma unroll
;   for (int d0 = 0; d0 < 6; ++d0) qf[d0] = *(const bf16x8*)(Q + (size_t)qrow * 1536 + h * 96 + d0 * 16 + 8 * hi);
;   const float C = 0.10206207261596577f * LOG2E;
; #pragma unroll
;   for (int j = 0; j < 8; ++j) {
;     const float c = ct[pos * 16 + 8 * hi + j], s = st[pos * 16 + 8 * hi + j];
;     const float t1 = bfs2f(qf[4][j]), t2 = bfs2f(qf[5][j]);
;     qf[4][j] = (short)f2bf((t1 * c - t2 * s) * C); qf[5][j] = (short)f2bf((t1 * s + t2 * c) * C);
;   }
; #pragma unroll
;   for (int d0 = 0; d0 < 4; ++d0)
; #pragma unroll
;     for (int j = 0; j < 8; ++j) qf[d0][j] = (short)f2bf(bfs2f(qf[d0][j]) * C);
;   const int srow = tid >> 3, sc = tid & 7, rrow = (tid >> 2) & 63, rc = tid & 3;
;   const bool kr_on = tid < 256;
;   const u16* kvsrc = KV + (size_t)(seqbase + srow) * KVP + h * 128 + sc * 8;
;   const u16* krsrc = KR + (size_t)(seqbase + rrow) * 32 + rc * 8;
;   const int kdst0 = srow * KP + sc * 8, kdst2 = rrow * KP + 64 + rc * 8, vdst = srow * VP + sc * 8;
;   float l_run = 0.f; f32x16 o0 = {}, o1 = {}, negm = {};
;   const int nkt = S >> 6;
;   u32x4 rkn, rkr, rvv;
;     ...
;   MLA_GLOAD(0); MLA_LSTORE(0);
;   MLA_GLOAD(1); MLA_LSTORE(1);
;   __syncthreads();
;   int cur = 0, nx2 = 2;
;   if (wid >= 4) __builtin_amdgcn_s_setprio(1);
.LBB0_1070:
	s_or_b64 exec, exec, s[46:47]
	s_waitcnt vmcnt(1)
	ds_write_b128 v179, v[100:103] offset:13312
	s_waitcnt vmcnt(0)
	ds_write_b128 v180, v[104:107] offset:52224
	s_and_saveexec_b64 s[46:47], s[0:1]
	ds_write_b128 v184, v[96:99] offset:13440
	s_or_b64 exec, exec, s[46:47]
	s_waitcnt lgkmcnt(0)
	s_barrier
	s_and_saveexec_b64 s[46:47], s[4:5]
	s_setprio 1
	s_or_b64 exec, exec, s[46:47]
	s_lshl_b32 s28, s48, 6
	s_and_b32 s28, s28, 0x800
	s_or_b32 s28, s28, s57
	v_lshlrev_b64 v[42:43], 6, v[50:51]
	v_mov_b32_e32 v0, s28
	v_lshl_add_u64 v[170:171], v[156:157], 0, v[42:43]
	v_subrev_u32_e32 v193, s24, v170
	v_mad_i64_i32 v[42:43], s[28:29], v56, s59, v[0:1]
	v_and_b32_e32 v45, 0xffff0000, v26
	v_lshlrev_b32_e32 v44, 16, v26
	v_lshl_add_u64 v[172:173], v[158:159], 0, v[42:43]
	v_subrev_u32_e32 v192, s24, v172
	v_and_b32_e32 v43, 0xffff0000, v30
	v_lshlrev_b32_e32 v42, 16, v30
	v_pk_mul_f32 v[46:47], v[34:35], v[44:45]
	v_lshlrev_b32_e32 v30, 16, v27
	v_pk_fma_f32 v[46:47], v[38:39], v[42:43], v[46:47]
	v_pk_mul_f32 v[38:39], v[38:39], v[44:45]
	v_pk_mul_f32 v[46:47], v[46:47], s[38:39] op_sel_hi:[1,0]
	v_pk_fma_f32 v[34:35], v[34:35], v[42:43], v[38:39] neg_lo:[0,0,1] neg_hi:[0,0,1]
	v_cvt_pk_bf16_f32 v108, v46, v47
	v_pk_mul_f32 v[34:35], v[34:35], s[38:39] op_sel_hi:[1,0]
	v_mov_b32_e32 v0, v1
	v_cvt_pk_bf16_f32 v112, v34, v35
	v_and_b32_e32 v35, 0xffff0000, v31
	v_lshlrev_b32_e32 v34, 16, v31
	v_and_b32_e32 v31, 0xffff0000, v27
	v_pk_mul_f32 v[26:27], v[40:41], v[34:35]
	v_ashrrev_i32_e32 v169, 31, v168
	v_pk_fma_f32 v[26:27], v[36:37], v[30:31], v[26:27]
	s_mov_b32 s36, 0
	v_pk_mul_f32 v[26:27], v[26:27], s[38:39] op_sel_hi:[1,0]
	s_mov_b32 s63, 2
	v_cvt_pk_bf16_f32 v109, v26, v27
	v_pk_mul_f32 v[26:27], v[40:41], v[30:31]
	v_and_b32_e32 v31, 0xffff0000, v28
	v_pk_fma_f32 v[26:27], v[36:37], v[34:35], v[26:27] neg_lo:[0,0,1] neg_hi:[0,0,1]
	v_lshlrev_b32_e32 v30, 16, v28
	v_pk_mul_f32 v[26:27], v[26:27], s[38:39] op_sel_hi:[1,0]
	v_mov_b32_e32 v153, 0
	v_cvt_pk_bf16_f32 v113, v26, v27
	v_and_b32_e32 v27, 0xffff0000, v32
	v_lshlrev_b32_e32 v26, 16, v32
	v_pk_mul_f32 v[34:35], v[22:23], v[26:27]
	v_pk_mul_f32 v[22:23], v[22:23], v[30:31]
	v_pk_fma_f32 v[34:35], v[18:19], v[30:31], v[34:35]
	v_pk_fma_f32 v[18:19], v[18:19], v[26:27], v[22:23] neg_lo:[0,0,1] neg_hi:[0,0,1]
	v_and_b32_e32 v23, 0xffff0000, v29
	v_pk_mul_f32 v[18:19], v[18:19], s[38:39] op_sel_hi:[1,0]
	v_lshlrev_b32_e32 v22, 16, v29
	v_cvt_pk_bf16_f32 v114, v18, v19
	v_and_b32_e32 v19, 0xffff0000, v33
	v_lshlrev_b32_e32 v18, 16, v33
	v_pk_mul_f32 v[26:27], v[24:25], v[18:19]
	v_pk_mul_f32 v[34:35], v[34:35], s[38:39] op_sel_hi:[1,0]
	v_pk_fma_f32 v[26:27], v[20:21], v[22:23], v[26:27]
	v_pk_mul_f32 v[22:23], v[24:25], v[22:23]
	v_pk_mul_f32 v[26:27], v[26:27], s[38:39] op_sel_hi:[1,0]
	v_pk_fma_f32 v[18:19], v[20:21], v[18:19], v[22:23] neg_lo:[0,0,1] neg_hi:[0,0,1]
	v_cvt_pk_bf16_f32 v110, v34, v35
	v_pk_mul_f32 v[18:19], v[18:19], s[38:39] op_sel_hi:[1,0]
	v_cvt_pk_bf16_f32 v111, v26, v27
	v_cvt_pk_bf16_f32 v115, v18, v19
	v_and_b32_e32 v19, 0xffff0000, v14
	v_lshlrev_b32_e32 v18, 16, v14
	v_pk_mul_f32 v[18:19], v[18:19], s[38:39] op_sel_hi:[1,0]
	s_mov_b64 s[46:47], 0
	s_mov_b64 s[98:99], s[24:25]
	v_cvt_pk_bf16_f32 v116, v18, v19
	v_and_b32_e32 v19, 0xffff0000, v15
	v_lshlrev_b32_e32 v18, 16, v15
	v_pk_mul_f32 v[14:15], v[18:19], s[38:39] op_sel_hi:[1,0]
	s_mov_b32 s64, 0
	v_cvt_pk_bf16_f32 v117, v14, v15
	v_and_b32_e32 v15, 0xffff0000, v16
	v_lshlrev_b32_e32 v14, 16, v16
	v_pk_mul_f32 v[14:15], v[14:15], s[38:39] op_sel_hi:[1,0]
	s_nop 0
	v_cvt_pk_bf16_f32 v118, v14, v15
	v_and_b32_e32 v15, 0xffff0000, v17
	v_lshlrev_b32_e32 v14, 16, v17
	v_pk_mul_f32 v[14:15], v[14:15], s[38:39] op_sel_hi:[1,0]
	s_nop 0
	v_cvt_pk_bf16_f32 v119, v14, v15
	v_and_b32_e32 v15, 0xffff0000, v10
	v_lshlrev_b32_e32 v14, 16, v10
	v_pk_mul_f32 v[14:15], v[14:15], s[38:39] op_sel_hi:[1,0]
	s_nop 0
	v_cvt_pk_bf16_f32 v120, v14, v15
	v_and_b32_e32 v15, 0xffff0000, v11
	v_lshlrev_b32_e32 v14, 16, v11
	v_pk_mul_f32 v[10:11], v[14:15], s[38:39] op_sel_hi:[1,0]
	v_mov_b32_e32 v14, v1
	v_cvt_pk_bf16_f32 v121, v10, v11
	v_and_b32_e32 v11, 0xffff0000, v12
	v_lshlrev_b32_e32 v10, 16, v12
	v_pk_mul_f32 v[10:11], v[10:11], s[38:39] op_sel_hi:[1,0]
	v_mov_b32_e32 v15, v1
	v_cvt_pk_bf16_f32 v122, v10, v11
	v_and_b32_e32 v11, 0xffff0000, v13
	v_lshlrev_b32_e32 v10, 16, v13
	v_pk_mul_f32 v[10:11], v[10:11], s[38:39] op_sel_hi:[1,0]
	v_mov_b32_e32 v12, v1
	v_cvt_pk_bf16_f32 v123, v10, v11
	v_and_b32_e32 v11, 0xffff0000, v6
	v_lshlrev_b32_e32 v10, 16, v6
	v_pk_mul_f32 v[10:11], v[10:11], s[38:39] op_sel_hi:[1,0]
	v_mov_b32_e32 v13, v1
	v_cvt_pk_bf16_f32 v124, v10, v11
	v_and_b32_e32 v11, 0xffff0000, v7
	v_lshlrev_b32_e32 v10, 16, v7
	v_pk_mul_f32 v[6:7], v[10:11], s[38:39] op_sel_hi:[1,0]
	v_mov_b32_e32 v10, v1
	v_cvt_pk_bf16_f32 v125, v6, v7
	v_and_b32_e32 v7, 0xffff0000, v8
	v_lshlrev_b32_e32 v6, 16, v8
	v_pk_mul_f32 v[6:7], v[6:7], s[38:39] op_sel_hi:[1,0]
	v_mov_b32_e32 v8, v1
	v_cvt_pk_bf16_f32 v126, v6, v7
	v_and_b32_e32 v7, 0xffff0000, v9
	v_lshlrev_b32_e32 v6, 16, v9
	v_pk_mul_f32 v[6:7], v[6:7], s[38:39] op_sel_hi:[1,0]
	v_mov_b32_e32 v9, v1
	v_cvt_pk_bf16_f32 v127, v6, v7
	v_and_b32_e32 v7, 0xffff0000, v2
	v_lshlrev_b32_e32 v6, 16, v2
	v_pk_mul_f32 v[6:7], v[6:7], s[38:39] op_sel_hi:[1,0]
	v_mov_b32_e32 v11, v1
	v_cvt_pk_bf16_f32 v128, v6, v7
	v_and_b32_e32 v7, 0xffff0000, v3
	v_lshlrev_b32_e32 v6, 16, v3
	v_pk_mul_f32 v[2:3], v[6:7], s[38:39] op_sel_hi:[1,0]
	v_mov_b32_e32 v6, v1
	v_cvt_pk_bf16_f32 v129, v2, v3
	v_and_b32_e32 v3, 0xffff0000, v4
	v_lshlrev_b32_e32 v2, 16, v4
	v_pk_mul_f32 v[2:3], v[2:3], s[38:39] op_sel_hi:[1,0]
	v_mov_b32_e32 v4, v1
	v_cvt_pk_bf16_f32 v130, v2, v3
	v_and_b32_e32 v3, 0xffff0000, v5
	v_lshlrev_b32_e32 v2, 16, v5
	v_pk_mul_f32 v[2:3], v[2:3], s[38:39] op_sel_hi:[1,0]
	v_mov_b32_e32 v5, v1
	v_cvt_pk_bf16_f32 v131, v2, v3
	v_mov_b32_e32 v2, v1
	v_mov_b32_e32 v3, v1
	v_mov_b32_e32 v7, v1
	v_mov_b64_e32 v[46:47], v[14:15]
	v_mov_b64_e32 v[30:31], v[14:15]
	v_mov_b64_e32 v[62:63], v[14:15]
	v_mov_b64_e32 v[44:45], v[12:13]
	v_mov_b64_e32 v[42:43], v[10:11]
	v_mov_b64_e32 v[40:41], v[8:9]
	v_mov_b64_e32 v[38:39], v[6:7]
	v_mov_b64_e32 v[36:37], v[4:5]
	v_mov_b64_e32 v[34:35], v[2:3]
	v_mov_b64_e32 v[32:33], v[0:1]
	v_mov_b64_e32 v[28:29], v[12:13]
	v_mov_b64_e32 v[26:27], v[10:11]
	v_mov_b64_e32 v[24:25], v[8:9]
	v_mov_b64_e32 v[22:23], v[6:7]
	v_mov_b64_e32 v[20:21], v[4:5]
	v_mov_b64_e32 v[18:19], v[2:3]
	v_mov_b64_e32 v[16:17], v[0:1]
	v_mov_b64_e32 v[60:61], v[12:13]
	v_mov_b64_e32 v[58:59], v[10:11]
	v_mov_b64_e32 v[56:57], v[8:9]
	v_mov_b64_e32 v[54:55], v[6:7]
	v_mov_b64_e32 v[52:53], v[4:5]
	v_mov_b64_e32 v[50:51], v[2:3]
	v_mov_b64_e32 v[48:49], v[0:1]
	s_branch .LBB0_1077

; #define MLA_GLOAD(T) do { rkn = *(const u32x4*)(kvsrc + (size_t)(T) * 64 * KVP); rvv = *(const u32x4*)(kvsrc + (size_t)(T) * 64 * KVP + 64); \
;     if (kr_on) rkr = *(const u32x4*)(krsrc + (size_t)(T) * 64 * 32); } while (0)
; #define MLA_LSTORE(B) do { u16* kd = Kl + (B) * 64 * KP; u16* vd = Vl + (B) * 64 * VP; *(u32x4*)(kd + kdst0) = rkn; *(u32x4*)(vd + vdst) = rvv; \
;     if (kr_on) *(u32x4*)(kd + kdst2) = rkr; } while (0)
; DI void mla_unit(const Params& p, char* lds, int seqbase, int S, int h, int qb) {
;     ...
;   MLA_GLOAD(0); MLA_LSTORE(0);
;   MLA_GLOAD(1); MLA_LSTORE(1);
;   __syncthreads();
;   int cur = 0, nx2 = 2;
;   if (wid >= 4) __builtin_amdgcn_s_setprio(1);
; #pragma unroll 1
;   for (int kt = 0; kt < nkt; ++kt) {
;     if (kt + 2 < nkt) MLA_GLOAD(kt + 2);
;     ...
;     cur = cur == 2 ? 0 : cur + 1; nx2 = nx2 == 2 ? 0 : nx2 + 1;
.LBB0_1076:
	s_add_i32 s28, s36, 1
	s_cmp_lg_u32 s36, 2
	s_cselect_b32 s36, s28, 0
	s_add_i32 s28, s63, 1
	s_cmp_lg_u32 s63, 2
	s_cselect_b32 s63, s28, 0
	s_add_i32 s64, s64, 1
	s_add_u32 s46, s46, 0x42000
	s_addc_u32 s47, s47, 0
	v_add_f32_e32 v153, v153, v0
	s_add_u32 s98, s98, 0x1000
	s_addc_u32 s99, s99, 0
	s_cmp_lg_u32 s46, 0x2100000
	s_cbranch_scc0 .LBB0_1063
.LBB0_1077:
	s_cmpk_lt_u32 s64, 0x7e
	s_cselect_b64 s[48:49], -1, 0
	s_cmpk_gt_u32 s64, 0x7d
	s_cbranch_scc1 .LBB0_1081
	s_add_u32 s100, s46, 0x12684000
	s_addc_u32 s101, s47, 0
	s_add_u32 s100, s100, s24
	s_addc_u32 s101, s101, s25
	global_load_dwordx4 v[100:103], v192, s[100:101]
	global_load_dwordx4 v[104:107], v192, s[100:101] offset:128
	s_and_saveexec_b64 s[50:51], s[0:1]
	s_cbranch_execz .LBB0_1080
	global_load_dwordx4 v[96:99], v193, s[98:99]

; DI float bfs2f(short v) { return __uint_as_float(((unsigned)(u16)v) << 16); }
; DI u16 f2bf(float a) { return (u16)(pk2(a, 0.f) & 0xffffu); }
; #define MLA_GLOAD(T) do { rkn = *(const u32x4*)(kvsrc + (size_t)(T) * 64 * KVP); rvv = *(const u32x4*)(kvsrc + (size_t)(T) * 64 * KVP + 64); \
;     if (kr_on) rkr = *(const u32x4*)(krsrc + (size_t)(T) * 64 * 32); } while (0)
; #define MLA_LSTORE(B) do { u16* kd = Kl + (B) * 64 * KP; u16* vd = Vl + (B) * 64 * VP; *(u32x4*)(kd + kdst0) = rkn; *(u32x4*)(vd + vdst) = rvv; \
;     if (kr_on) *(u32x4*)(kd + kdst2) = rkr; } while (0)
; DI void mla_unit(const Params& p, char* lds, int seqbase, int S, int h, int qb) {
;     ...
;   const float C = 0.10206207261596577f * LOG2E;
; #pragma unroll
;   for (int j = 0; j < 8; ++j) {
;     const float c = ct[pos * 16 + 8 * hi + j], s = st[pos * 16 + 8 * hi + j];
;     const float t1 = bfs2f(qf[4][j]), t2 = bfs2f(qf[5][j]);
;     qf[4][j] = (short)f2bf((t1 * c - t2 * s) * C); qf[5][j] = (short)f2bf((t1 * s + t2 * c) * C);
;   }
; #pragma unroll
;   for (int d0 = 0; d0 < 4; ++d0)
; #pragma unroll
;     for (int j = 0; j < 8; ++j) qf[d0][j] = (short)f2bf(bfs2f(qf[d0][j]) * C);
;   const int srow = tid >> 3, sc = tid & 7, rrow = (tid >> 2) & 63, rc = tid & 3;
;   const bool kr_on = tid < 256;
;   const u16* kvsrc = KV + (size_t)(seqbase + srow) * KVP + h * 128 + sc * 8;
;   const u16* krsrc = KR + (size_t)(seqbase + rrow) * 32 + rc * 8;
;   const int kdst0 = srow * KP + sc * 8, kdst2 = rrow * KP + 64 + rc * 8, vdst = srow * VP + sc * 8;
;   float l_run = 0.f; f32x16 o0 = {}, o1 = {}, negm = {};
;   const int nkt = S >> 6;
;   u32x4 rkn, rkr, rvv;
;     ...
;   MLA_GLOAD(0); MLA_LSTORE(0);
;   MLA_GLOAD(1); MLA_LSTORE(1);
;   __syncthreads();
;   int cur = 0, nx2 = 2;
;   if (wid >= 4) __builtin_amdgcn_s_setprio(1);
.LBB0_1100:
	s_or_b64 exec, exec, s[38:39]
	s_waitcnt vmcnt(1)
	ds_write_b128 v179, v[102:105] offset:13312
	s_waitcnt vmcnt(0)
	ds_write_b128 v180, v[106:109] offset:52224
	s_and_saveexec_b64 s[38:39], s[0:1]
	ds_write_b128 v184, v[98:101] offset:13440
	s_or_b64 exec, exec, s[38:39]
	s_waitcnt lgkmcnt(0)
	s_barrier
	s_and_saveexec_b64 s[38:39], s[4:5]
	s_setprio 1
	s_or_b64 exec, exec, s[38:39]
	v_add_u32_e32 v44, s41, v186
	s_and_b32 s18, s40, 0x800
	v_ashrrev_i32_e32 v45, 31, v44
	s_or_b32 s18, s18, s57
	v_lshlrev_b64 v[44:45], 6, v[44:45]
	v_add_u32_e32 v1, s41, v187
	v_mov_b32_e32 v2, s18
	v_lshl_add_u64 v[170:171], v[156:157], 0, v[44:45]
	v_subrev_u32_e32 v193, s24, v170
	v_mad_i64_i32 v[44:45], s[28:29], v1, s54, v[2:3]
	v_and_b32_e32 v47, 0xffff0000, v28
	v_lshlrev_b32_e32 v46, 16, v28
	v_lshl_add_u64 v[172:173], v[158:159], 0, v[44:45]
	v_subrev_u32_e32 v192, s24, v172
	v_and_b32_e32 v45, 0xffff0000, v32
	v_lshlrev_b32_e32 v44, 16, v32
	v_pk_mul_f32 v[48:49], v[36:37], v[46:47]
	v_lshlrev_b32_e32 v32, 16, v29
	v_pk_fma_f32 v[48:49], v[40:41], v[44:45], v[48:49]
	v_pk_mul_f32 v[40:41], v[40:41], v[46:47]
	v_pk_mul_f32 v[48:49], v[48:49], s[20:21] op_sel_hi:[1,0]
	v_pk_fma_f32 v[36:37], v[36:37], v[44:45], v[40:41] neg_lo:[0,0,1] neg_hi:[0,0,1]
	v_cvt_pk_bf16_f32 v110, v48, v49
	v_pk_mul_f32 v[36:37], v[36:37], s[20:21] op_sel_hi:[1,0]
	v_mov_b32_e32 v2, v3
	v_cvt_pk_bf16_f32 v114, v36, v37
	v_and_b32_e32 v37, 0xffff0000, v33
	v_lshlrev_b32_e32 v36, 16, v33
	v_and_b32_e32 v33, 0xffff0000, v29
	v_pk_mul_f32 v[28:29], v[42:43], v[36:37]
	v_ashrrev_i32_e32 v169, 31, v168
	v_pk_fma_f32 v[28:29], v[38:39], v[32:33], v[28:29]
	s_mov_b32 s18, 0
	v_pk_mul_f32 v[28:29], v[28:29], s[20:21] op_sel_hi:[1,0]
	s_mov_b32 s58, 2
	v_cvt_pk_bf16_f32 v111, v28, v29
	v_pk_mul_f32 v[28:29], v[42:43], v[32:33]
	v_and_b32_e32 v33, 0xffff0000, v30
	v_pk_fma_f32 v[28:29], v[38:39], v[36:37], v[28:29] neg_lo:[0,0,1] neg_hi:[0,0,1]
	v_lshlrev_b32_e32 v32, 16, v30
	v_pk_mul_f32 v[28:29], v[28:29], s[20:21] op_sel_hi:[1,0]
	v_mov_b32_e32 v1, 0
	v_cvt_pk_bf16_f32 v115, v28, v29
	v_and_b32_e32 v29, 0xffff0000, v34
	v_lshlrev_b32_e32 v28, 16, v34
	v_pk_mul_f32 v[36:37], v[24:25], v[28:29]
	v_pk_mul_f32 v[24:25], v[24:25], v[32:33]
	v_pk_fma_f32 v[36:37], v[20:21], v[32:33], v[36:37]
	v_pk_fma_f32 v[20:21], v[20:21], v[28:29], v[24:25] neg_lo:[0,0,1] neg_hi:[0,0,1]
	v_and_b32_e32 v25, 0xffff0000, v31
	v_pk_mul_f32 v[20:21], v[20:21], s[20:21] op_sel_hi:[1,0]
	v_lshlrev_b32_e32 v24, 16, v31
	v_cvt_pk_bf16_f32 v116, v20, v21
	v_and_b32_e32 v21, 0xffff0000, v35
	v_lshlrev_b32_e32 v20, 16, v35
	v_pk_mul_f32 v[28:29], v[26:27], v[20:21]
	v_pk_mul_f32 v[36:37], v[36:37], s[20:21] op_sel_hi:[1,0]
	v_pk_fma_f32 v[28:29], v[22:23], v[24:25], v[28:29]
	v_pk_mul_f32 v[24:25], v[26:27], v[24:25]
	v_pk_mul_f32 v[28:29], v[28:29], s[20:21] op_sel_hi:[1,0]
	v_pk_fma_f32 v[20:21], v[22:23], v[20:21], v[24:25] neg_lo:[0,0,1] neg_hi:[0,0,1]
	v_cvt_pk_bf16_f32 v112, v36, v37
	v_pk_mul_f32 v[20:21], v[20:21], s[20:21] op_sel_hi:[1,0]
	v_cvt_pk_bf16_f32 v113, v28, v29
	v_cvt_pk_bf16_f32 v117, v20, v21
	v_and_b32_e32 v21, 0xffff0000, v16
	v_lshlrev_b32_e32 v20, 16, v16
	v_pk_mul_f32 v[20:21], v[20:21], s[20:21] op_sel_hi:[1,0]
	s_mov_b64 s[38:39], 0
	s_mov_b64 s[98:99], s[24:25]
	v_cvt_pk_bf16_f32 v118, v20, v21
	v_and_b32_e32 v21, 0xffff0000, v17
	v_lshlrev_b32_e32 v20, 16, v17
	v_pk_mul_f32 v[16:17], v[20:21], s[20:21] op_sel_hi:[1,0]
	s_mov_b32 s59, 0
	v_cvt_pk_bf16_f32 v119, v16, v17
	v_and_b32_e32 v17, 0xffff0000, v18
	v_lshlrev_b32_e32 v16, 16, v18
	v_pk_mul_f32 v[16:17], v[16:17], s[20:21] op_sel_hi:[1,0]
	s_nop 0
	v_cvt_pk_bf16_f32 v120, v16, v17
	v_and_b32_e32 v17, 0xffff0000, v19
	v_lshlrev_b32_e32 v16, 16, v19
	v_pk_mul_f32 v[16:17], v[16:17], s[20:21] op_sel_hi:[1,0]
	s_nop 0
	v_cvt_pk_bf16_f32 v121, v16, v17
	v_and_b32_e32 v17, 0xffff0000, v12
	v_lshlrev_b32_e32 v16, 16, v12
	v_pk_mul_f32 v[16:17], v[16:17], s[20:21] op_sel_hi:[1,0]
	s_nop 0
	v_cvt_pk_bf16_f32 v122, v16, v17
	v_and_b32_e32 v17, 0xffff0000, v13
	v_lshlrev_b32_e32 v16, 16, v13
	v_pk_mul_f32 v[12:13], v[16:17], s[20:21] op_sel_hi:[1,0]
	v_mov_b32_e32 v16, v3
	v_cvt_pk_bf16_f32 v123, v12, v13
	v_and_b32_e32 v13, 0xffff0000, v14
	v_lshlrev_b32_e32 v12, 16, v14
	v_pk_mul_f32 v[12:13], v[12:13], s[20:21] op_sel_hi:[1,0]
	v_mov_b32_e32 v17, v3
	v_cvt_pk_bf16_f32 v124, v12, v13
	v_and_b32_e32 v13, 0xffff0000, v15
	v_lshlrev_b32_e32 v12, 16, v15
	v_pk_mul_f32 v[12:13], v[12:13], s[20:21] op_sel_hi:[1,0]
	v_mov_b32_e32 v14, v3
	v_cvt_pk_bf16_f32 v125, v12, v13
	v_and_b32_e32 v13, 0xffff0000, v8
	v_lshlrev_b32_e32 v12, 16, v8
	v_pk_mul_f32 v[12:13], v[12:13], s[20:21] op_sel_hi:[1,0]
	v_mov_b32_e32 v15, v3
	v_cvt_pk_bf16_f32 v126, v12, v13
	v_and_b32_e32 v13, 0xffff0000, v9
	v_lshlrev_b32_e32 v12, 16, v9
	v_pk_mul_f32 v[8:9], v[12:13], s[20:21] op_sel_hi:[1,0]
	v_mov_b32_e32 v12, v3
	v_cvt_pk_bf16_f32 v127, v8, v9
	v_and_b32_e32 v9, 0xffff0000, v10
	v_lshlrev_b32_e32 v8, 16, v10
	v_pk_mul_f32 v[8:9], v[8:9], s[20:21] op_sel_hi:[1,0]
	v_mov_b32_e32 v10, v3
	v_cvt_pk_bf16_f32 v128, v8, v9
	v_and_b32_e32 v9, 0xffff0000, v11
	v_lshlrev_b32_e32 v8, 16, v11
	v_pk_mul_f32 v[8:9], v[8:9], s[20:21] op_sel_hi:[1,0]
	v_mov_b32_e32 v11, v3
	v_cvt_pk_bf16_f32 v129, v8, v9
	v_and_b32_e32 v9, 0xffff0000, v4
	v_lshlrev_b32_e32 v8, 16, v4
	v_pk_mul_f32 v[8:9], v[8:9], s[20:21] op_sel_hi:[1,0]
	v_mov_b32_e32 v13, v3
	v_cvt_pk_bf16_f32 v130, v8, v9
	v_and_b32_e32 v9, 0xffff0000, v5
	v_lshlrev_b32_e32 v8, 16, v5
	v_pk_mul_f32 v[4:5], v[8:9], s[20:21] op_sel_hi:[1,0]
	v_mov_b32_e32 v8, v3
	v_cvt_pk_bf16_f32 v131, v4, v5
	v_and_b32_e32 v5, 0xffff0000, v6
	v_lshlrev_b32_e32 v4, 16, v6
	v_pk_mul_f32 v[4:5], v[4:5], s[20:21] op_sel_hi:[1,0]
	v_mov_b32_e32 v6, v3
	v_cvt_pk_bf16_f32 v132, v4, v5
	v_and_b32_e32 v5, 0xffff0000, v7
	v_lshlrev_b32_e32 v4, 16, v7
	v_pk_mul_f32 v[4:5], v[4:5], s[20:21] op_sel_hi:[1,0]
	v_mov_b32_e32 v7, v3
	v_cvt_pk_bf16_f32 v133, v4, v5
	v_mov_b32_e32 v4, v3
	v_mov_b32_e32 v5, v3
	v_mov_b32_e32 v9, v3
	v_mov_b64_e32 v[48:49], v[16:17]
	v_mov_b64_e32 v[32:33], v[16:17]
	v_mov_b64_e32 v[64:65], v[16:17]
	v_mov_b64_e32 v[46:47], v[14:15]
	v_mov_b64_e32 v[44:45], v[12:13]
	v_mov_b64_e32 v[42:43], v[10:11]
	v_mov_b64_e32 v[40:41], v[8:9]
	v_mov_b64_e32 v[38:39], v[6:7]
	v_mov_b64_e32 v[36:37], v[4:5]
	v_mov_b64_e32 v[34:35], v[2:3]
	v_mov_b64_e32 v[30:31], v[14:15]
	v_mov_b64_e32 v[28:29], v[12:13]
	v_mov_b64_e32 v[26:27], v[10:11]
	v_mov_b64_e32 v[24:25], v[8:9]
	v_mov_b64_e32 v[22:23], v[6:7]
	v_mov_b64_e32 v[20:21], v[4:5]
	v_mov_b64_e32 v[18:19], v[2:3]
	v_mov_b64_e32 v[62:63], v[14:15]
	v_mov_b64_e32 v[60:61], v[12:13]
	v_mov_b64_e32 v[58:59], v[10:11]
	v_mov_b64_e32 v[56:57], v[8:9]
	v_mov_b64_e32 v[54:55], v[6:7]
	v_mov_b64_e32 v[52:53], v[4:5]
	v_mov_b64_e32 v[50:51], v[2:3]
	s_branch .LBB0_1107

; #define MLA_GLOAD(T) do { rkn = *(const u32x4*)(kvsrc + (size_t)(T) * 64 * KVP); rvv = *(const u32x4*)(kvsrc + (size_t)(T) * 64 * KVP + 64); \
;     if (kr_on) rkr = *(const u32x4*)(krsrc + (size_t)(T) * 64 * 32); } while (0)
; #define MLA_LSTORE(B) do { u16* kd = Kl + (B) * 64 * KP; u16* vd = Vl + (B) * 64 * VP; *(u32x4*)(kd + kdst0) = rkn; *(u32x4*)(vd + vdst) = rvv; \
;     if (kr_on) *(u32x4*)(kd + kdst2) = rkr; } while (0)
; DI void mla_unit(const Params& p, char* lds, int seqbase, int S, int h, int qb) {
;     ...
;   MLA_GLOAD(0); MLA_LSTORE(0);
;   MLA_GLOAD(1); MLA_LSTORE(1);
;   __syncthreads();
;   int cur = 0, nx2 = 2;
;   if (wid >= 4) __builtin_amdgcn_s_setprio(1);
; #pragma unroll 1
;   for (int kt = 0; kt < nkt; ++kt) {
;     if (kt + 2 < nkt) MLA_GLOAD(kt + 2);
;     ...
;     cur = cur == 2 ? 0 : cur + 1; nx2 = nx2 == 2 ? 0 : nx2 + 1;
.LBB0_1106:
	s_add_i32 s28, s18, 1
	s_cmp_lg_u32 s18, 2
	s_cselect_b32 s18, s28, 0
	s_add_i32 s28, s58, 1
	s_cmp_lg_u32 s58, 2
	s_cselect_b32 s58, s28, 0
	s_add_i32 s59, s59, 1
	s_add_u32 s38, s38, 0x42000
	s_addc_u32 s39, s39, 0
	v_add_f32_e32 v1, v1, v2
	s_add_u32 s98, s98, 0x1000
	s_addc_u32 s99, s99, 0
	s_cmp_lg_u32 s38, 0x1080000
	s_cbranch_scc0 .LBB0_1093
.LBB0_1107:
	s_cmp_lt_u32 s59, 62
	s_cselect_b64 s[40:41], -1, 0
	s_cmp_gt_u32 s59, 61
	s_cbranch_scc1 .LBB0_1111
	s_add_u32 s100, s38, 0x12684000
	s_addc_u32 s101, s39, 0
	s_add_u32 s100, s100, s24
	s_addc_u32 s101, s101, s25
	global_load_dwordx4 v[102:105], v192, s[100:101]
	global_load_dwordx4 v[106:109], v192, s[100:101] offset:128
	s_and_saveexec_b64 s[46:47], s[0:1]
	s_cbranch_execz .LBB0_1110
	global_load_dwordx4 v[98:101], v193, s[98:99]
